# prologue-A weight conversion (layer 0) hand-rewritten: 15 items in 3 rounds of 5 with 40+ loads in flight instead of 13 serial load-store rounds
# baseline (speedup 1.0000x reference)
.LBB0_20:
	v_writelane_b32 v253, s68, 40
	s_lshl_b32 s0, s80, 9
	v_add_u32_e32 v10, s0, v8
	v_writelane_b32 v253, s69, 41
	v_writelane_b32 v253, s70, 42
	v_writelane_b32 v253, s71, 43
	v_writelane_b32 v253, s72, 44
	v_writelane_b32 v253, s73, 45
	v_writelane_b32 v253, s74, 46
	v_writelane_b32 v253, s75, 47
	v_writelane_b32 v253, s0, 48
	s_lshl_b32 s92, s96, 9
	s_mov_b64 s[2:3], exec
	v_readlane_b32 s8, v253, 20
	v_readlane_b32 s9, v253, 21
	v_readlane_b32 s10, v253, 30
	v_readlane_b32 s11, v253, 31
	v_readlane_b32 s12, v253, 28
	v_readlane_b32 s13, v253, 29
	v_readlane_b32 s14, v253, 34
	v_readlane_b32 s15, v253, 35
	v_readlane_b32 s16, v253, 32
	v_readlane_b32 s17, v253, 33
	v_readlane_b32 s18, v253, 36
	v_readlane_b32 s19, v253, 37
	v_readlane_b32 s20, v253, 38
	v_readlane_b32 s21, v253, 39
	v_mov_b32_e32 v11, 0
	v_mov_b32_e32 v192, v10
	v_cmp_gt_u32_e32 vcc, 0x6d000, v192
	s_mov_b64 s[36:37], vcc
	s_mov_b32 s1, 0x12c9fc
	v_mul_hi_u32 v193, v192, s1
	v_mul_u32_u24_e32 v194, 0xda0, v193
	v_sub_u32_e32 v194, v192, v194
	v_mul_u32_u24_e32 v195, 0x37400, v193
	v_lshl_add_u32 v195, v194, 2, v195
	v_lshlrev_b32_e32 v196, 11, v194
	v_lshl_add_u32 v196, v193, 4, v196
	v_add_u32_e32 v196, 0x400000, v196
	s_mov_b64 exec, s[36:37]
	global_load_dword v104, v195, s[8:9]
	v_add_u32_e32 v195, 0x6e80, v195
	global_load_dword v105, v195, s[8:9]
	v_add_u32_e32 v195, 0x6e80, v195
	global_load_dword v106, v195, s[8:9]
	v_add_u32_e32 v195, 0x6e80, v195
	global_load_dword v107, v195, s[8:9]
	v_add_u32_e32 v195, 0x6e80, v195
	global_load_dword v108, v195, s[8:9]
	v_add_u32_e32 v195, 0x6e80, v195
	global_load_dword v109, v195, s[8:9]
	v_add_u32_e32 v195, 0x6e80, v195
	global_load_dword v110, v195, s[8:9]
	v_add_u32_e32 v195, 0x6e80, v195
	global_load_dword v111, v195, s[8:9]
	s_mov_b64 exec, s[2:3]
	s_mul_i32 s0, s92, 1
	v_add_u32_e32 v200, s0, v10
	v_cmp_gt_u32_e32 vcc, 0x6d000, v200
	s_mov_b64 s[38:39], vcc
	s_mov_b32 s1, 0x12c9fc
	v_mul_hi_u32 v201, v200, s1
	v_mul_u32_u24_e32 v202, 0xda0, v201
	v_sub_u32_e32 v202, v200, v202
	v_mul_u32_u24_e32 v203, 0x37400, v201
	v_lshl_add_u32 v203, v202, 2, v203
	v_lshlrev_b32_e32 v204, 11, v202
	v_lshl_add_u32 v204, v201, 4, v204
	v_add_u32_e32 v204, 0x400000, v204
	s_mov_b64 exec, s[38:39]
	global_load_dword v120, v203, s[8:9]
	v_add_u32_e32 v203, 0x6e80, v203
	global_load_dword v121, v203, s[8:9]
	v_add_u32_e32 v203, 0x6e80, v203
	global_load_dword v122, v203, s[8:9]
	v_add_u32_e32 v203, 0x6e80, v203
	global_load_dword v123, v203, s[8:9]
	v_add_u32_e32 v203, 0x6e80, v203
	global_load_dword v124, v203, s[8:9]
	v_add_u32_e32 v203, 0x6e80, v203
	global_load_dword v125, v203, s[8:9]
	v_add_u32_e32 v203, 0x6e80, v203
	global_load_dword v126, v203, s[8:9]
	v_add_u32_e32 v203, 0x6e80, v203
	global_load_dword v127, v203, s[8:9]
	s_mov_b64 exec, s[2:3]
	v_mov_b32_e32 v208, v10
	v_cmp_gt_u32_e32 vcc, 0x70000, v208
	s_mov_b64 s[40:41], vcc
	s_mov_b32 s1, 0x124925
	v_mul_hi_u32 v209, v208, s1
	v_mul_u32_u24_e32 v210, 0xe00, v209
	v_sub_u32_e32 v210, v208, v210
	v_mul_u32_u24_e32 v211, 0x37400, v209
	v_lshl_add_u32 v211, v210, 2, v211
	v_add_u32_e32 v211, 0x3680, v211
	v_lshlrev_b32_e32 v212, 11, v210
	v_lshl_add_u32 v212, v209, 4, v212
	v_add_u32_e32 v212, 0xb00000, v212
	s_mov_b64 exec, s[40:41]
	global_load_dword v136, v211, s[8:9]
	v_add_u32_e32 v211, 0x6e80, v211
	global_load_dword v137, v211, s[8:9]
	v_add_u32_e32 v211, 0x6e80, v211
	global_load_dword v138, v211, s[8:9]
	v_add_u32_e32 v211, 0x6e80, v211
	global_load_dword v139, v211, s[8:9]
	v_add_u32_e32 v211, 0x6e80, v211
	global_load_dword v140, v211, s[8:9]
	v_add_u32_e32 v211, 0x6e80, v211
	global_load_dword v141, v211, s[8:9]
	v_add_u32_e32 v211, 0x6e80, v211
	global_load_dword v142, v211, s[8:9]
	v_add_u32_e32 v211, 0x6e80, v211
	global_load_dword v143, v211, s[8:9]
	s_mov_b64 exec, s[2:3]
	s_mul_i32 s0, s92, 1
	v_add_u32_e32 v216, s0, v10
	v_cmp_gt_u32_e32 vcc, 0x70000, v216
	s_mov_b64 s[42:43], vcc
	s_mov_b32 s1, 0x124925
	v_mul_hi_u32 v217, v216, s1
	v_mul_u32_u24_e32 v218, 0xe00, v217
	v_sub_u32_e32 v218, v216, v218
	v_mul_u32_u24_e32 v219, 0x37400, v217
	v_lshl_add_u32 v219, v218, 2, v219
	v_add_u32_e32 v219, 0x3680, v219
	v_lshlrev_b32_e32 v220, 11, v218
	v_lshl_add_u32 v220, v217, 4, v220
	v_add_u32_e32 v220, 0xb00000, v220
	s_mov_b64 exec, s[42:43]
	global_load_dword v152, v219, s[8:9]
	v_add_u32_e32 v219, 0x6e80, v219
	global_load_dword v153, v219, s[8:9]
	v_add_u32_e32 v219, 0x6e80, v219
	global_load_dword v154, v219, s[8:9]
	v_add_u32_e32 v219, 0x6e80, v219
	global_load_dword v155, v219, s[8:9]
	v_add_u32_e32 v219, 0x6e80, v219
	global_load_dword v156, v219, s[8:9]
	v_add_u32_e32 v219, 0x6e80, v219
	global_load_dword v157, v219, s[8:9]
	v_add_u32_e32 v219, 0x6e80, v219
	global_load_dword v158, v219, s[8:9]
	v_add_u32_e32 v219, 0x6e80, v219
	global_load_dword v159, v219, s[8:9]
	s_mov_b64 exec, s[2:3]
	v_mov_b32_e32 v224, v10
	v_cmp_gt_u32_e32 vcc, 0x20000, v224
	s_mov_b64 s[44:45], vcc
	v_lshrrev_b32_e32 v225, 10, v224
	v_and_b32_e32 v226, 0x3ff, v224
	v_mul_u32_u24_e32 v227, 0x8000, v225
	v_lshl_add_u32 v227, v226, 2, v227
	v_lshlrev_b32_e32 v228, 11, v226
	v_lshl_add_u32 v228, v225, 4, v228
	v_add_u32_e32 v228, 0x1700000, v228
	s_mov_b64 exec, s[44:45]
	global_load_dword v176, v227, s[70:71]
	v_add_u32_e32 v227, 0x1000, v227
	global_load_dword v177, v227, s[70:71]
	v_add_u32_e32 v227, 0x1000, v227
	global_load_dword v178, v227, s[70:71]
	v_add_u32_e32 v227, 0x1000, v227
	global_load_dword v179, v227, s[70:71]
	v_add_u32_e32 v227, 0x1000, v227
	global_load_dword v180, v227, s[70:71]
	v_add_u32_e32 v227, 0x1000, v227
	global_load_dword v181, v227, s[70:71]
	v_add_u32_e32 v227, 0x1000, v227
	global_load_dword v182, v227, s[70:71]
	v_add_u32_e32 v227, 0x1000, v227
	global_load_dword v183, v227, s[70:71]
	s_mov_b64 exec, s[2:3]
	s_waitcnt vmcnt(0)
	s_mov_b64 exec, s[36:37]
	v_cvt_pk_bf16_f32 v104, v104, v105
	v_cvt_pk_bf16_f32 v105, v106, v107
	v_cvt_pk_bf16_f32 v106, v108, v109
	v_cvt_pk_bf16_f32 v107, v110, v111
	global_store_dwordx4 v196, v[104:107], s[94:95]
	s_mov_b64 exec, s[2:3]
	s_mov_b64 exec, s[38:39]
	v_cvt_pk_bf16_f32 v120, v120, v121
	v_cvt_pk_bf16_f32 v121, v122, v123
	v_cvt_pk_bf16_f32 v122, v124, v125
	v_cvt_pk_bf16_f32 v123, v126, v127
	global_store_dwordx4 v204, v[120:123], s[94:95]
	s_mov_b64 exec, s[2:3]
	s_mov_b64 exec, s[40:41]
	v_cvt_pk_bf16_f32 v136, v136, v137
	v_cvt_pk_bf16_f32 v137, v138, v139
	v_cvt_pk_bf16_f32 v138, v140, v141
	v_cvt_pk_bf16_f32 v139, v142, v143
	global_store_dwordx4 v212, v[136:139], s[94:95]
	s_mov_b64 exec, s[2:3]
	s_mov_b64 exec, s[42:43]
	v_cvt_pk_bf16_f32 v152, v152, v153
	v_cvt_pk_bf16_f32 v153, v154, v155
	v_cvt_pk_bf16_f32 v154, v156, v157
	v_cvt_pk_bf16_f32 v155, v158, v159
	global_store_dwordx4 v220, v[152:155], s[94:95]
	s_mov_b64 exec, s[2:3]
	s_mov_b64 exec, s[44:45]
	v_cvt_pk_bf16_f32 v176, v176, v177
	v_cvt_pk_bf16_f32 v177, v178, v179
	v_cvt_pk_bf16_f32 v178, v180, v181
	v_cvt_pk_bf16_f32 v179, v182, v183
	global_store_dwordx4 v228, v[176:179], s[94:95]
	s_mov_b64 exec, s[2:3]
	s_mul_i32 s0, s92, 2
	v_add_u32_e32 v192, s0, v10
	v_cmp_gt_u32_e32 vcc, 0x6d000, v192
	s_mov_b64 s[36:37], vcc
	s_mov_b32 s1, 0x12c9fc
	v_mul_hi_u32 v193, v192, s1
	v_mul_u32_u24_e32 v194, 0xda0, v193
	v_sub_u32_e32 v194, v192, v194
	v_mul_u32_u24_e32 v195, 0x37400, v193
	v_lshl_add_u32 v195, v194, 2, v195
	v_lshlrev_b32_e32 v196, 11, v194
	v_lshl_add_u32 v196, v193, 4, v196
	v_add_u32_e32 v196, 0x400000, v196
	s_mov_b64 exec, s[36:37]
	global_load_dword v104, v195, s[8:9]
	v_add_u32_e32 v195, 0x6e80, v195
	global_load_dword v105, v195, s[8:9]
	v_add_u32_e32 v195, 0x6e80, v195
	global_load_dword v106, v195, s[8:9]
	v_add_u32_e32 v195, 0x6e80, v195
	global_load_dword v107, v195, s[8:9]
	v_add_u32_e32 v195, 0x6e80, v195
	global_load_dword v108, v195, s[8:9]
	v_add_u32_e32 v195, 0x6e80, v195
	global_load_dword v109, v195, s[8:9]
	v_add_u32_e32 v195, 0x6e80, v195
	global_load_dword v110, v195, s[8:9]
	v_add_u32_e32 v195, 0x6e80, v195
	global_load_dword v111, v195, s[8:9]
	s_mov_b64 exec, s[2:3]
	s_mul_i32 s0, s92, 3
	v_add_u32_e32 v200, s0, v10
	v_cmp_gt_u32_e32 vcc, 0x6d000, v200
	s_mov_b64 s[38:39], vcc
	s_mov_b32 s1, 0x12c9fc
	v_mul_hi_u32 v201, v200, s1
	v_mul_u32_u24_e32 v202, 0xda0, v201
	v_sub_u32_e32 v202, v200, v202
	v_mul_u32_u24_e32 v203, 0x37400, v201
	v_lshl_add_u32 v203, v202, 2, v203
	v_lshlrev_b32_e32 v204, 11, v202
	v_lshl_add_u32 v204, v201, 4, v204
	v_add_u32_e32 v204, 0x400000, v204
	s_mov_b64 exec, s[38:39]
	global_load_dword v120, v203, s[8:9]
	v_add_u32_e32 v203, 0x6e80, v203
	global_load_dword v121, v203, s[8:9]
	v_add_u32_e32 v203, 0x6e80, v203
	global_load_dword v122, v203, s[8:9]
	v_add_u32_e32 v203, 0x6e80, v203
	global_load_dword v123, v203, s[8:9]
	v_add_u32_e32 v203, 0x6e80, v203
	global_load_dword v124, v203, s[8:9]
	v_add_u32_e32 v203, 0x6e80, v203
	global_load_dword v125, v203, s[8:9]
	v_add_u32_e32 v203, 0x6e80, v203
	global_load_dword v126, v203, s[8:9]
	v_add_u32_e32 v203, 0x6e80, v203
	global_load_dword v127, v203, s[8:9]
	s_mov_b64 exec, s[2:3]
	s_mul_i32 s0, s92, 2
	v_add_u32_e32 v208, s0, v10
	v_cmp_gt_u32_e32 vcc, 0x70000, v208
	s_mov_b64 s[40:41], vcc
	s_mov_b32 s1, 0x124925
	v_mul_hi_u32 v209, v208, s1
	v_mul_u32_u24_e32 v210, 0xe00, v209
	v_sub_u32_e32 v210, v208, v210
	v_mul_u32_u24_e32 v211, 0x37400, v209
	v_lshl_add_u32 v211, v210, 2, v211
	v_add_u32_e32 v211, 0x3680, v211
	v_lshlrev_b32_e32 v212, 11, v210
	v_lshl_add_u32 v212, v209, 4, v212
	v_add_u32_e32 v212, 0xb00000, v212
	s_mov_b64 exec, s[40:41]
	global_load_dword v136, v211, s[8:9]
	v_add_u32_e32 v211, 0x6e80, v211
	global_load_dword v137, v211, s[8:9]
	v_add_u32_e32 v211, 0x6e80, v211
	global_load_dword v138, v211, s[8:9]
	v_add_u32_e32 v211, 0x6e80, v211
	global_load_dword v139, v211, s[8:9]
	v_add_u32_e32 v211, 0x6e80, v211
	global_load_dword v140, v211, s[8:9]
	v_add_u32_e32 v211, 0x6e80, v211
	global_load_dword v141, v211, s[8:9]
	v_add_u32_e32 v211, 0x6e80, v211
	global_load_dword v142, v211, s[8:9]
	v_add_u32_e32 v211, 0x6e80, v211
	global_load_dword v143, v211, s[8:9]
	s_mov_b64 exec, s[2:3]
	s_mul_i32 s0, s92, 3
	v_add_u32_e32 v216, s0, v10
	v_cmp_gt_u32_e32 vcc, 0x70000, v216
	s_mov_b64 s[42:43], vcc
	s_mov_b32 s1, 0x124925
	v_mul_hi_u32 v217, v216, s1
	v_mul_u32_u24_e32 v218, 0xe00, v217
	v_sub_u32_e32 v218, v216, v218
	v_mul_u32_u24_e32 v219, 0x37400, v217
	v_lshl_add_u32 v219, v218, 2, v219
	v_add_u32_e32 v219, 0x3680, v219
	v_lshlrev_b32_e32 v220, 11, v218
	v_lshl_add_u32 v220, v217, 4, v220
	v_add_u32_e32 v220, 0xb00000, v220
	s_mov_b64 exec, s[42:43]
	global_load_dword v152, v219, s[8:9]
	v_add_u32_e32 v219, 0x6e80, v219
	global_load_dword v153, v219, s[8:9]
	v_add_u32_e32 v219, 0x6e80, v219
	global_load_dword v154, v219, s[8:9]
	v_add_u32_e32 v219, 0x6e80, v219
	global_load_dword v155, v219, s[8:9]
	v_add_u32_e32 v219, 0x6e80, v219
	global_load_dword v156, v219, s[8:9]
	v_add_u32_e32 v219, 0x6e80, v219
	global_load_dword v157, v219, s[8:9]
	v_add_u32_e32 v219, 0x6e80, v219
	global_load_dword v158, v219, s[8:9]
	v_add_u32_e32 v219, 0x6e80, v219
	global_load_dword v159, v219, s[8:9]
	s_mov_b64 exec, s[2:3]
	v_mov_b32_e32 v224, v10
	v_cmp_gt_u32_e32 vcc, 0x8000, v224
	s_mov_b64 s[44:45], vcc
	v_lshrrev_b32_e32 v225, 9, v224
	v_and_b32_e32 v226, 0x1ff, v224
	v_mul_u32_u24_e32 v227, 0x4000, v225
	v_lshl_add_u32 v227, v226, 2, v227
	v_lshlrev_b32_e32 v228, 10, v226
	v_lshl_add_u32 v228, v225, 4, v228
	v_add_u32_e32 v228, 0x1300000, v228
	s_mov_b64 exec, s[44:45]
	global_load_dword v176, v227, s[66:67]
	v_add_u32_e32 v227, 0x800, v227
	global_load_dword v177, v227, s[66:67]
	v_add_u32_e32 v227, 0x800, v227
	global_load_dword v178, v227, s[66:67]
	v_add_u32_e32 v227, 0x800, v227
	global_load_dword v179, v227, s[66:67]
	v_add_u32_e32 v227, 0x800, v227
	global_load_dword v180, v227, s[66:67]
	v_add_u32_e32 v227, 0x800, v227
	global_load_dword v181, v227, s[66:67]
	v_add_u32_e32 v227, 0x800, v227
	global_load_dword v182, v227, s[66:67]
	v_add_u32_e32 v227, 0x800, v227
	global_load_dword v183, v227, s[66:67]
	s_mov_b64 exec, s[2:3]
	s_waitcnt vmcnt(0)
	s_mov_b64 exec, s[36:37]
	v_cvt_pk_bf16_f32 v104, v104, v105
	v_cvt_pk_bf16_f32 v105, v106, v107
	v_cvt_pk_bf16_f32 v106, v108, v109
	v_cvt_pk_bf16_f32 v107, v110, v111
	global_store_dwordx4 v196, v[104:107], s[94:95]
	s_mov_b64 exec, s[2:3]
	s_mov_b64 exec, s[38:39]
	v_cvt_pk_bf16_f32 v120, v120, v121
	v_cvt_pk_bf16_f32 v121, v122, v123
	v_cvt_pk_bf16_f32 v122, v124, v125
	v_cvt_pk_bf16_f32 v123, v126, v127
	global_store_dwordx4 v204, v[120:123], s[94:95]
	s_mov_b64 exec, s[2:3]
	s_mov_b64 exec, s[40:41]
	v_cvt_pk_bf16_f32 v136, v136, v137
	v_cvt_pk_bf16_f32 v137, v138, v139
	v_cvt_pk_bf16_f32 v138, v140, v141
	v_cvt_pk_bf16_f32 v139, v142, v143
	global_store_dwordx4 v212, v[136:139], s[94:95]
	s_mov_b64 exec, s[2:3]
	s_mov_b64 exec, s[42:43]
	v_cvt_pk_bf16_f32 v152, v152, v153
	v_cvt_pk_bf16_f32 v153, v154, v155
	v_cvt_pk_bf16_f32 v154, v156, v157
	v_cvt_pk_bf16_f32 v155, v158, v159
	global_store_dwordx4 v220, v[152:155], s[94:95]
	s_mov_b64 exec, s[2:3]
	s_mov_b64 exec, s[44:45]
	v_cvt_pk_bf16_f32 v176, v176, v177
	v_cvt_pk_bf16_f32 v177, v178, v179
	v_cvt_pk_bf16_f32 v178, v180, v181
	v_cvt_pk_bf16_f32 v179, v182, v183
	global_store_dwordx4 v228, v[176:179], s[94:95]
	s_mov_b64 exec, s[2:3]
	v_mov_b32_e32 v192, v10
	v_cmp_gt_u32_e32 vcc, 0x6000, v192
	s_mov_b64 s[36:37], vcc
	s_mov_b32 s1, 0x555556
	v_mul_hi_u32 v193, v192, s1
	v_mul_u32_u24_e32 v194, 0x300, v193
	v_sub_u32_e32 v194, v192, v194
	v_mul_u32_u24_e32 v195, 0x6000, v193
	v_lshl_add_u32 v195, v194, 2, v195
	v_lshlrev_b32_e32 v196, 9, v194
	v_lshl_add_u32 v196, v193, 4, v196
	v_add_u32_e32 v196, 0x1200000, v196
	v_lshlrev_b32_e32 v197, 5, v193
	s_mov_b64 exec, s[36:37]
	global_load_dword v104, v195, s[10:11]
	v_add_u32_e32 v195, 0xc00, v195
	global_load_dword v105, v195, s[10:11]
	v_add_u32_e32 v195, 0xc00, v195
	global_load_dword v106, v195, s[10:11]
	v_add_u32_e32 v195, 0xc00, v195
	global_load_dword v107, v195, s[10:11]
	v_add_u32_e32 v195, 0xc00, v195
	global_load_dword v108, v195, s[10:11]
	v_add_u32_e32 v195, 0xc00, v195
	global_load_dword v109, v195, s[10:11]
	v_add_u32_e32 v195, 0xc00, v195
	global_load_dword v110, v195, s[10:11]
	v_add_u32_e32 v195, 0xc00, v195
	global_load_dword v111, v195, s[10:11]
	global_load_dwordx4 v[112:115], v197, s[12:13]
	global_load_dwordx4 v[116:119], v197, s[12:13] offset:16
	s_mov_b64 exec, s[2:3]
	v_mov_b32_e32 v200, v10
	v_cmp_gt_u32_e32 vcc, 0x4000, v200
	s_mov_b64 s[38:39], vcc
	v_lshrrev_b32_e32 v201, 10, v200
	v_and_b32_e32 v202, 0x3ff, v200
	v_mul_u32_u24_e32 v203, 0x8000, v201
	v_lshl_add_u32 v203, v202, 2, v203
	v_lshlrev_b32_e32 v204, 8, v202
	v_lshl_add_u32 v204, v201, 4, v204
	v_add_u32_e32 v204, 0x1280000, v204
	v_lshlrev_b32_e32 v205, 5, v201
	s_mov_b64 exec, s[38:39]
	global_load_dword v120, v203, s[14:15]
	v_add_u32_e32 v203, 0x1000, v203
	global_load_dword v121, v203, s[14:15]
	v_add_u32_e32 v203, 0x1000, v203
	global_load_dword v122, v203, s[14:15]
	v_add_u32_e32 v203, 0x1000, v203
	global_load_dword v123, v203, s[14:15]
	v_add_u32_e32 v203, 0x1000, v203
	global_load_dword v124, v203, s[14:15]
	v_add_u32_e32 v203, 0x1000, v203
	global_load_dword v125, v203, s[14:15]
	v_add_u32_e32 v203, 0x1000, v203
	global_load_dword v126, v203, s[14:15]
	v_add_u32_e32 v203, 0x1000, v203
	global_load_dword v127, v203, s[14:15]
	global_load_dwordx4 v[128:131], v205, s[16:17]
	global_load_dwordx4 v[132:135], v205, s[16:17] offset:16
	s_mov_b64 exec, s[2:3]
	v_mov_b32_e32 v208, v10
	v_cmp_gt_u32_e32 vcc, 0x10000, v208
	s_mov_b64 s[40:41], vcc
	v_lshrrev_b32_e32 v209, 10, v208
	v_and_b32_e32 v210, 0x3ff, v208
	v_mul_u32_u24_e32 v211, 0x8000, v209
	v_lshl_add_u32 v211, v210, 2, v211
	v_lshlrev_b32_e32 v212, 10, v210
	v_lshl_add_u32 v212, v209, 4, v212
	v_add_u32_e32 v212, 0x1400000, v212
	s_mov_b64 exec, s[40:41]
	global_load_dword v136, v211, s[18:19]
	v_add_u32_e32 v211, 0x1000, v211
	global_load_dword v137, v211, s[18:19]
	v_add_u32_e32 v211, 0x1000, v211
	global_load_dword v138, v211, s[18:19]
	v_add_u32_e32 v211, 0x1000, v211
	global_load_dword v139, v211, s[18:19]
	v_add_u32_e32 v211, 0x1000, v211
	global_load_dword v140, v211, s[18:19]
	v_add_u32_e32 v211, 0x1000, v211
	global_load_dword v141, v211, s[18:19]
	v_add_u32_e32 v211, 0x1000, v211
	global_load_dword v142, v211, s[18:19]
	v_add_u32_e32 v211, 0x1000, v211
	global_load_dword v143, v211, s[18:19]
	s_mov_b64 exec, s[2:3]
	v_mov_b32_e32 v216, v10
	v_cmp_gt_u32_e32 vcc, 0x10000, v216
	s_mov_b64 s[42:43], vcc
	v_lshrrev_b32_e32 v217, 10, v216
	v_and_b32_e32 v218, 0x3ff, v216
	v_mul_u32_u24_e32 v219, 0x8000, v217
	v_lshl_add_u32 v219, v218, 2, v219
	v_lshlrev_b32_e32 v220, 10, v218
	v_lshl_add_u32 v220, v217, 4, v220
	v_add_u32_e32 v220, 0x1500000, v220
	s_mov_b64 exec, s[42:43]
	global_load_dword v152, v219, s[20:21]
	v_add_u32_e32 v219, 0x1000, v219
	global_load_dword v153, v219, s[20:21]
	v_add_u32_e32 v219, 0x1000, v219
	global_load_dword v154, v219, s[20:21]
	v_add_u32_e32 v219, 0x1000, v219
	global_load_dword v155, v219, s[20:21]
	v_add_u32_e32 v219, 0x1000, v219
	global_load_dword v156, v219, s[20:21]
	v_add_u32_e32 v219, 0x1000, v219
	global_load_dword v157, v219, s[20:21]
	v_add_u32_e32 v219, 0x1000, v219
	global_load_dword v158, v219, s[20:21]
	v_add_u32_e32 v219, 0x1000, v219
	global_load_dword v159, v219, s[20:21]
	s_mov_b64 exec, s[2:3]
	v_mov_b32_e32 v224, v10
	v_cmp_gt_u32_e32 vcc, 0x10000, v224
	s_mov_b64 s[44:45], vcc
	v_lshrrev_b32_e32 v225, 10, v224
	v_and_b32_e32 v226, 0x3ff, v224
	v_mul_u32_u24_e32 v227, 0x8000, v225
	v_lshl_add_u32 v227, v226, 2, v227
	v_lshlrev_b32_e32 v228, 10, v226
	v_lshl_add_u32 v228, v225, 4, v228
	v_add_u32_e32 v228, 0x1600000, v228
	s_mov_b64 exec, s[44:45]
	global_load_dword v176, v227, s[68:69]
	v_add_u32_e32 v227, 0x1000, v227
	global_load_dword v177, v227, s[68:69]
	v_add_u32_e32 v227, 0x1000, v227
	global_load_dword v178, v227, s[68:69]
	v_add_u32_e32 v227, 0x1000, v227
	global_load_dword v179, v227, s[68:69]
	v_add_u32_e32 v227, 0x1000, v227
	global_load_dword v180, v227, s[68:69]
	v_add_u32_e32 v227, 0x1000, v227
	global_load_dword v181, v227, s[68:69]
	v_add_u32_e32 v227, 0x1000, v227
	global_load_dword v182, v227, s[68:69]
	v_add_u32_e32 v227, 0x1000, v227
	global_load_dword v183, v227, s[68:69]
	s_mov_b64 exec, s[2:3]
	s_waitcnt vmcnt(0)
	s_mov_b64 exec, s[36:37]
	v_mul_f32_e32 v104, v104, v112
	v_mul_f32_e32 v105, v105, v113
	v_mul_f32_e32 v106, v106, v114
	v_mul_f32_e32 v107, v107, v115
	v_mul_f32_e32 v108, v108, v116
	v_mul_f32_e32 v109, v109, v117
	v_mul_f32_e32 v110, v110, v118
	v_mul_f32_e32 v111, v111, v119
	v_cvt_pk_bf16_f32 v104, v104, v105
	v_cvt_pk_bf16_f32 v105, v106, v107
	v_cvt_pk_bf16_f32 v106, v108, v109
	v_cvt_pk_bf16_f32 v107, v110, v111
	global_store_dwordx4 v196, v[104:107], s[94:95]
	s_mov_b64 exec, s[2:3]
	s_mov_b64 exec, s[38:39]
	v_mul_f32_e32 v120, v120, v128
	v_mul_f32_e32 v121, v121, v129
	v_mul_f32_e32 v122, v122, v130
	v_mul_f32_e32 v123, v123, v131
	v_mul_f32_e32 v124, v124, v132
	v_mul_f32_e32 v125, v125, v133
	v_mul_f32_e32 v126, v126, v134
	v_mul_f32_e32 v127, v127, v135
	v_cvt_pk_bf16_f32 v120, v120, v121
	v_cvt_pk_bf16_f32 v121, v122, v123
	v_cvt_pk_bf16_f32 v122, v124, v125
	v_cvt_pk_bf16_f32 v123, v126, v127
	global_store_dwordx4 v204, v[120:123], s[94:95]
	s_mov_b64 exec, s[2:3]
	s_mov_b64 exec, s[40:41]
	v_cvt_pk_bf16_f32 v136, v136, v137
	v_cvt_pk_bf16_f32 v137, v138, v139
	v_cvt_pk_bf16_f32 v138, v140, v141
	v_cvt_pk_bf16_f32 v139, v142, v143
	global_store_dwordx4 v212, v[136:139], s[94:95]
	s_mov_b64 exec, s[2:3]
	s_mov_b64 exec, s[42:43]
	v_cvt_pk_bf16_f32 v152, v152, v153
	v_cvt_pk_bf16_f32 v153, v154, v155
	v_cvt_pk_bf16_f32 v154, v156, v157
	v_cvt_pk_bf16_f32 v155, v158, v159
	global_store_dwordx4 v220, v[152:155], s[94:95]
	s_mov_b64 exec, s[2:3]
	s_mov_b64 exec, s[44:45]
	v_cvt_pk_bf16_f32 v176, v176, v177
	v_cvt_pk_bf16_f32 v177, v178, v179
	v_cvt_pk_bf16_f32 v178, v180, v181
	v_cvt_pk_bf16_f32 v179, v182, v183
	global_store_dwordx4 v228, v[176:179], s[94:95]
	s_mov_b64 exec, s[2:3]
	v_cmp_gt_u32_e32 vcc, 0x3000, v10
	v_lshlrev_b32_e32 v192, 4, v10
	v_add_u32_e32 v192, 0xad0000, v192
	v_mov_b32_e32 v104, 0
	v_mov_b32_e32 v105, 0
	v_mov_b32_e32 v106, 0
	v_mov_b32_e32 v107, 0
	s_and_b64 exec, s[2:3], vcc
	global_store_dwordx4 v192, v[104:107], s[94:95]
	s_mov_b64 exec, s[2:3]
